# attention epilogue: the four attn_norm loads of a round issued together under the PV MFMAs (3 load/vmcnt(0) round trips per round removed)
# speedup vs baseline: 1.0332x; 1.0150x over previous
.LBB0_446:
	s_add_i32 s16, s16, s2
	s_max_i32 s11, s16, 4
	s_ashr_i32 s10, s15, 8
	s_add_i32 s11, s11, -4
	s_min_u32 s1, s17, 49
	s_min_u32 s12, s11, 56
	s_ashr_i32 s11, s10, 31
	s_and_b32 s0, s14, 48
	s_sub_i32 s13, s12, s1
	s_lshl_b64 s[10:11], s[10:11], 12
	s_lshl_b32 s1, s16, 6
	s_add_u32 s10, s10, s1
	s_addc_u32 s1, s11, 0
	s_lshl_b32 s46, s13, 12
	v_add_u32_e32 v83, s46, v182
	v_add_u32_e32 v129, v83, v177
	v_add_u32_e32 v131, v83, v178
	ds_read_b128 v[84:87], v129
	ds_read_b128 v[88:91], v129 offset:512
	ds_read_b128 v[92:95], v131
	ds_read_b128 v[96:99], v131 offset:512
	s_waitcnt vmcnt(18) lgkmcnt(3)
	v_mfma_f32_16x16x32_bf16 v[84:87], v[84:87], v[78:81], 0
	v_sub_u32_e64 v82, s0, 8 clamp
	v_min_u32_e32 v133, 32, v82
	v_or_b32_e32 v135, s0, v173
	s_waitcnt lgkmcnt(2)
	v_mfma_f32_16x16x32_bf16 v[88:91], v[88:91], v[78:81], 0
	s_or_b32 s0, s10, s0
	s_lshl_b64 s[0:1], s[0:1], 11
	s_add_i32 s47, s46, 0x1000
	s_waitcnt lgkmcnt(1)
	v_mfma_f32_16x16x32_bf16 v[188:191], v[92:95], v[74:77], v[84:87]
	s_add_i32 s45, s46, 0x2000
	s_add_i32 s44, s46, 0x3000
	s_add_i32 s43, s46, 0x4000
	s_waitcnt lgkmcnt(0)
	v_mfma_f32_16x16x32_bf16 v[192:195], v[96:99], v[74:77], v[88:91]
	ds_read_b128 v[84:87], v129 offset:4096
	s_nop 1
	ds_read_b128 v[88:91], v129 offset:4608
	ds_read_b128 v[92:95], v131 offset:4096
	ds_read_b128 v[96:99], v131 offset:4608
	s_add_i32 s42, s46, 0x5000
	s_waitcnt lgkmcnt(3)
	v_mfma_f32_16x16x32_bf16 v[84:87], v[84:87], v[78:81], 0
	s_add_i32 s41, s46, 0x6000
	s_add_i32 s40, s46, 0x7000
	s_add_u32 s38, s80, s0
	s_waitcnt lgkmcnt(1)
	v_mfma_f32_16x16x32_bf16 v[196:199], v[92:95], v[74:77], v[84:87]
	s_addc_u32 s39, s81, s1
	s_sub_i32 s0, s12, s16
	s_mulk_i32 s0, 0x7c
	v_mfma_f32_16x16x32_bf16 v[84:87], v[88:91], v[78:81], 0
	s_add_i32 s0, s0, 0
	s_add_i32 s0, s0, 0x1e100
	s_waitcnt lgkmcnt(0)
	v_mfma_f32_16x16x32_bf16 v[200:203], v[96:99], v[74:77], v[84:87]
	s_nop 3
	ds_read_b128 v[84:87], v129 offset:8192
	ds_read_b128 v[88:91], v129 offset:8704
	ds_read_b128 v[92:95], v131 offset:8192
	ds_read_b128 v[96:99], v131 offset:8704
	s_waitcnt lgkmcnt(3)
	v_mfma_f32_16x16x32_bf16 v[84:87], v[84:87], v[78:81], 0
	s_waitcnt lgkmcnt(1)
	v_mfma_f32_16x16x32_bf16 v[122:125], v[92:95], v[74:77], v[84:87]
	ds_read_b128 v[92:95], v131 offset:12288
	v_mfma_f32_16x16x32_bf16 v[84:87], v[88:91], v[78:81], 0
	ds_read_b128 v[88:91], v129 offset:12288
	s_waitcnt lgkmcnt(2)
	v_mfma_f32_16x16x32_bf16 v[118:121], v[96:99], v[74:77], v[84:87]
	v_max_i32_e32 v96, 8, v135
	v_add_u32_e32 v137, -8, v96
	ds_read_b128 v[96:99], v131 offset:12800
	s_nop 1
	ds_read_b128 v[82:85], v129 offset:12800
	s_waitcnt lgkmcnt(2)
	v_mfma_f32_16x16x32_bf16 v[86:89], v[88:91], v[78:81], 0
	v_mfma_f32_16x16x32_bf16 v[110:113], v[92:95], v[74:77], v[86:89]
	ds_read_b128 v[90:93], v131 offset:16384
	s_nop 5
	ds_read_b128 v[86:89], v129 offset:16384
	s_waitcnt lgkmcnt(2)
	v_mfma_f32_16x16x32_bf16 v[82:85], v[82:85], v[78:81], 0
	v_mfma_f32_16x16x32_bf16 v[114:117], v[96:99], v[74:77], v[82:85]
	s_nop 6
	ds_read_b128 v[82:85], v129 offset:16896
	ds_read_b128 v[94:97], v131 offset:16896
	ds_read_b128 v[98:101], v129 offset:20480
	ds_read_b128 v[204:207], v129 offset:20992
	s_waitcnt lgkmcnt(4)
	v_mfma_f32_16x16x32_bf16 v[86:89], v[86:89], v[78:81], 0
	s_waitcnt lgkmcnt(3)
	v_mfma_f32_16x16x32_bf16 v[82:85], v[82:85], v[78:81], 0
	v_mfma_f32_16x16x32_bf16 v[102:105], v[90:93], v[74:77], v[86:89]
	s_nop 4
	ds_read_b128 v[86:89], v131 offset:20480
	ds_read_b128 v[90:93], v131 offset:20992
	ds_read_b128 v[208:211], v129 offset:24576
	ds_read_b128 v[212:215], v129 offset:25088
	ds_read_b128 v[216:219], v131 offset:24576
	ds_read_b128 v[220:223], v131 offset:25088
	ds_read_b128 v[224:227], v129 offset:28672
	ds_read_b128 v[228:231], v129 offset:29184
	s_waitcnt lgkmcnt(10)
	v_mfma_f32_16x16x32_bf16 v[106:109], v[94:97], v[74:77], v[82:85]
	ds_read_b128 v[232:235], v131 offset:28672
	ds_read_b128 v[236:239], v131 offset:29184
	v_add_u32_e32 v131, v133, v142
	v_min_u32_e32 v129, 48, v137
	s_waitcnt lgkmcnt(11)
	v_mfma_f32_16x16x32_bf16 v[82:85], v[98:101], v[78:81], 0
	v_cmp_ge_u32_e32 vcc, v131, v129
	v_or_b32_e32 v139, 1, v131
	v_or_b32_e32 v155, 2, v131
	s_waitcnt lgkmcnt(9)
	v_mfma_f32_16x16x32_bf16 v[94:97], v[86:89], v[74:77], v[82:85]
	v_or_b32_e32 v157, 3, v131
	v_mfma_f32_16x16x32_bf16 v[82:85], v[204:207], v[78:81], 0
	s_waitcnt lgkmcnt(8)
	v_mfma_f32_16x16x32_bf16 v[90:93], v[90:93], v[74:77], v[82:85]
	s_waitcnt lgkmcnt(6)
	v_mfma_f32_16x16x32_bf16 v[86:89], v[212:215], v[78:81], 0
	s_nop 3
	v_sub_u32_e32 v82, v131, v135
	v_lshl_add_u32 v133, v82, 2, s0
	ds_read2_b32 v[204:205], v133 offset0:232 offset1:233
	v_add_u32_e32 v135, 16, v129
	v_cmp_lt_u32_e64 s[0:1], v131, v135
	s_and_b64 vcc, vcc, s[0:1]
	v_mfma_f32_16x16x32_bf16 v[82:85], v[208:211], v[78:81], 0
	s_waitcnt lgkmcnt(0)
	v_add_f32_e32 v98, v188, v204
	v_cndmask_b32_e32 v137, v186, v98, vcc
	ds_read2_b32 v[206:207], v133 offset0:234 offset1:235
	ds_read2_b32 v[208:209], v133 offset0:236 offset1:237
	ds_read2_b32 v[210:211], v133 offset0:238 offset1:239
	v_mfma_f32_16x16x32_bf16 v[98:101], v[220:223], v[74:77], v[86:89]
	v_cmp_ge_u32_e64 s[0:1], v139, v129
	v_cmp_lt_u32_e64 s[10:11], v139, v135
	s_and_b64 s[10:11], s[0:1], s[10:11]
	v_mfma_f32_16x16x32_bf16 v[86:89], v[224:227], v[78:81], 0
	v_cmp_ge_u32_e64 s[0:1], v155, v129
	v_cmp_lt_u32_e64 s[12:13], v155, v135
	v_add_f32_e32 v139, v189, v205
	v_mfma_f32_16x16x32_bf16 v[78:81], v[228:231], v[78:81], 0
	s_and_b64 s[12:13], s[0:1], s[12:13]
	v_cmp_ge_u32_e64 s[0:1], v157, v129
	v_cmp_lt_u32_e64 s[14:15], v157, v135
	v_mfma_f32_16x16x32_bf16 v[82:85], v[216:219], v[74:77], v[82:85]
	v_cndmask_b32_e64 v139, v186, v139, s[10:11]
	s_waitcnt lgkmcnt(2)
	v_add_f32_e32 v155, v190, v206
	s_and_b64 s[14:15], s[0:1], s[14:15]
	v_mfma_f32_16x16x32_bf16 v[86:89], v[232:235], v[74:77], v[86:89]
	v_max3_f32 v141, v137, s33, v139
	v_cndmask_b32_e64 v155, v186, v155, s[12:13]
	v_add_u32_e32 v190, 0x434, v133
	v_mfma_f32_16x16x32_bf16 v[74:77], v[236:239], v[74:77], v[78:81]
	s_nop 2
	v_or_b32_e32 v79, 4, v131
	v_add_f32_e32 v78, v191, v207
	v_cmp_ge_u32_e64 s[0:1], v79, v129
	v_cmp_lt_u32_e64 s[16:17], v79, v135
	v_cndmask_b32_e64 v157, v186, v78, s[14:15]
	s_waitcnt lgkmcnt(1)
	v_add_f32_e32 v79, v192, v208
	s_and_b64 s[16:17], s[0:1], s[16:17]
	v_max3_f32 v78, v141, v155, v157
	v_cndmask_b32_e64 v141, v186, v79, s[16:17]
	v_or_b32_e32 v79, 5, v131
	v_cmp_ge_u32_e64 s[0:1], v79, v129
	v_cmp_lt_u32_e64 s[18:19], v79, v135
	v_add_f32_e32 v79, v193, v209
	s_and_b64 s[18:19], s[0:1], s[18:19]
	v_cndmask_b32_e64 v187, v186, v79, s[18:19]
	v_or_b32_e32 v79, 6, v131
	v_cmp_ge_u32_e64 s[0:1], v79, v129
	v_cmp_lt_u32_e64 s[20:21], v79, v135
	s_waitcnt lgkmcnt(0)
	v_add_f32_e32 v79, v194, v210
	s_and_b64 s[20:21], s[0:1], s[20:21]
	v_cndmask_b32_e64 v192, v186, v79, s[20:21]
	v_or_b32_e32 v79, 7, v131
	v_cmp_ge_u32_e64 s[0:1], v79, v129
	v_cmp_lt_u32_e64 s[22:23], v79, v135
	v_add_f32_e32 v79, v195, v211
	s_and_b64 s[22:23], s[0:1], s[22:23]
	v_max3_f32 v78, v78, v141, v187
	v_cndmask_b32_e64 v129, v186, v79, s[22:23]
	v_max3_f32 v131, v78, v192, v129
	v_add_u32_e32 v78, 0x41c, v133
	ds_read2_b32 v[78:79], v78 offset1:1
	v_add_u32_e32 v80, 0x424, v133
	v_add_u32_e32 v135, 0x42c, v133
	ds_read2_b32 v[80:81], v80 offset1:1
	ds_read2_b32 v[188:189], v135 offset1:1
	ds_read2_b32 v[190:191], v190 offset1:1
	s_lshl_b32 s0, s37, 7
	s_waitcnt lgkmcnt(3)
	v_add_f32_e32 v78, v196, v78
	v_cndmask_b32_e32 v135, v186, v78, vcc
	v_add_f32_e32 v78, v197, v79
	v_cndmask_b32_e64 v193, v186, v78, s[10:11]
	s_waitcnt lgkmcnt(2)
	v_add_f32_e32 v79, v198, v80
	v_max3_f32 v78, v131, v135, v193
	v_cndmask_b32_e64 v131, v186, v79, s[12:13]
	v_add_f32_e32 v79, v199, v81
	v_cndmask_b32_e64 v194, v186, v79, s[14:15]
	s_waitcnt lgkmcnt(1)
	v_add_f32_e32 v79, v200, v188
	v_cndmask_b32_e64 v195, v186, v79, s[16:17]
	v_add_f32_e32 v79, v201, v189
	v_cndmask_b32_e64 v196, v186, v79, s[18:19]
	s_waitcnt lgkmcnt(0)
	v_add_f32_e32 v79, v202, v190
	v_max3_f32 v78, v78, v131, v194
	v_cndmask_b32_e64 v197, v186, v79, s[20:21]
	v_add_f32_e32 v79, v203, v191
	v_max3_f32 v78, v78, v195, v196
	v_cndmask_b32_e64 v198, v186, v79, s[22:23]
	v_max3_f32 v199, v78, v197, v198
	v_add_u32_e32 v78, 0x498, v133
	ds_read2_b32 v[78:79], v78 offset1:1
	v_add_u32_e32 v80, 0x4a0, v133
	v_add_u32_e32 v188, 0x4a8, v133
	v_add_u32_e32 v190, 0x4b0, v133
	ds_read2_b32 v[80:81], v80 offset1:1
	ds_read2_b32 v[188:189], v188 offset1:1
	ds_read2_b32 v[190:191], v190 offset1:1
	s_waitcnt lgkmcnt(3)
	v_add_f32_e32 v78, v122, v78
	v_cndmask_b32_e32 v122, v186, v78, vcc
	v_add_f32_e32 v78, v123, v79
	s_waitcnt lgkmcnt(2)
	v_add_f32_e32 v79, v124, v80
	v_cndmask_b32_e64 v124, v186, v79, s[12:13]
	v_add_f32_e32 v79, v125, v81
	v_cndmask_b32_e64 v125, v186, v79, s[14:15]
	s_waitcnt lgkmcnt(1)
	v_add_f32_e32 v79, v118, v188
	v_cndmask_b32_e64 v123, v186, v78, s[10:11]
	v_cndmask_b32_e64 v188, v186, v79, s[16:17]
	v_add_f32_e32 v79, v119, v189
	v_max3_f32 v78, v199, v122, v123
	v_cndmask_b32_e64 v189, v186, v79, s[18:19]
	s_waitcnt lgkmcnt(0)
	v_add_f32_e32 v79, v120, v190
	v_max3_f32 v78, v78, v124, v125
	v_cndmask_b32_e64 v190, v186, v79, s[20:21]
	v_add_f32_e32 v79, v121, v191
	v_max3_f32 v78, v78, v188, v189
	v_cndmask_b32_e64 v191, v186, v79, s[22:23]
	v_max3_f32 v199, v78, v190, v191
	v_add_u32_e32 v78, 0x514, v133
	ds_read2_b32 v[78:79], v78 offset1:1
	v_add_u32_e32 v80, 0x51c, v133
	v_add_u32_e32 v118, 0x524, v133
	v_add_u32_e32 v120, 0x52c, v133
	ds_read2_b32 v[80:81], v80 offset1:1
	ds_read2_b32 v[118:119], v118 offset1:1
	ds_read2_b32 v[120:121], v120 offset1:1
	s_waitcnt lgkmcnt(3)
	v_add_f32_e32 v78, v110, v78
	v_cndmask_b32_e32 v200, v186, v78, vcc
	v_add_f32_e32 v78, v111, v79
	v_cndmask_b32_e64 v201, v186, v78, s[10:11]
	s_waitcnt lgkmcnt(2)
	v_add_f32_e32 v79, v112, v80
	v_max3_f32 v78, v199, v200, v201
	v_cndmask_b32_e64 v199, v186, v79, s[12:13]
	v_add_f32_e32 v79, v113, v81
	v_cndmask_b32_e64 v202, v186, v79, s[14:15]
	s_waitcnt lgkmcnt(1)
	v_add_f32_e32 v79, v114, v118
	v_cndmask_b32_e64 v114, v186, v79, s[16:17]
	v_add_f32_e32 v79, v115, v119
	v_cndmask_b32_e64 v115, v186, v79, s[18:19]
	s_waitcnt lgkmcnt(0)
	v_add_f32_e32 v79, v116, v120
	v_max3_f32 v78, v78, v199, v202
	v_cndmask_b32_e64 v116, v186, v79, s[20:21]
	v_add_f32_e32 v79, v117, v121
	v_max3_f32 v78, v78, v114, v115
	v_cndmask_b32_e64 v117, v186, v79, s[22:23]
	v_max3_f32 v118, v78, v116, v117
	v_add_u32_e32 v78, 0x590, v133
	ds_read2_b32 v[78:79], v78 offset1:1
	v_add_u32_e32 v80, 0x598, v133
	v_add_u32_e32 v110, 0x5a0, v133
	v_add_u32_e32 v112, 0x5a8, v133
	ds_read2_b32 v[80:81], v80 offset1:1
	ds_read2_b32 v[110:111], v110 offset1:1
	ds_read2_b32 v[112:113], v112 offset1:1
	s_waitcnt lgkmcnt(3)
	v_add_f32_e32 v78, v102, v78
	v_cndmask_b32_e32 v119, v186, v78, vcc
	v_add_f32_e32 v78, v103, v79
	v_cndmask_b32_e64 v120, v186, v78, s[10:11]
	s_waitcnt lgkmcnt(2)
	v_add_f32_e32 v79, v104, v80
	v_max3_f32 v78, v118, v119, v120
	v_cndmask_b32_e64 v118, v186, v79, s[12:13]
	v_add_f32_e32 v79, v105, v81
	v_cndmask_b32_e64 v121, v186, v79, s[14:15]
	s_waitcnt lgkmcnt(1)
	v_add_f32_e32 v79, v106, v110
	v_cndmask_b32_e64 v106, v186, v79, s[16:17]
	v_add_f32_e32 v79, v107, v111
	v_cndmask_b32_e64 v107, v186, v79, s[18:19]
	s_waitcnt lgkmcnt(0)
	v_add_f32_e32 v79, v108, v112
	v_max3_f32 v78, v78, v118, v121
	v_cndmask_b32_e64 v108, v186, v79, s[20:21]
	v_add_f32_e32 v79, v109, v113
	v_max3_f32 v78, v78, v106, v107
	v_cndmask_b32_e64 v109, v186, v79, s[22:23]
	v_max3_f32 v110, v78, v108, v109
	v_add_u32_e32 v78, 0x60c, v133
	ds_read2_b32 v[78:79], v78 offset1:1
	v_add_u32_e32 v80, 0x614, v133
	v_add_u32_e32 v102, 0x61c, v133
	v_add_u32_e32 v104, 0x624, v133
	ds_read2_b32 v[80:81], v80 offset1:1
	ds_read2_b32 v[102:103], v102 offset1:1
	ds_read2_b32 v[104:105], v104 offset1:1
	s_waitcnt lgkmcnt(3)
	v_add_f32_e32 v78, v94, v78
	v_cndmask_b32_e32 v94, v186, v78, vcc
	v_add_f32_e32 v78, v95, v79
	s_waitcnt lgkmcnt(2)
	v_add_f32_e32 v79, v96, v80
	v_cndmask_b32_e64 v96, v186, v79, s[12:13]
	v_add_f32_e32 v79, v97, v81
	v_cndmask_b32_e64 v97, v186, v79, s[14:15]
	s_waitcnt lgkmcnt(1)
	v_add_f32_e32 v79, v90, v102
	v_cndmask_b32_e64 v95, v186, v78, s[10:11]
	v_cndmask_b32_e64 v102, v186, v79, s[16:17]
	v_add_f32_e32 v79, v91, v103
	v_max3_f32 v78, v110, v94, v95
	v_cndmask_b32_e64 v103, v186, v79, s[18:19]
	s_waitcnt lgkmcnt(0)
	v_add_f32_e32 v79, v92, v104
	v_max3_f32 v78, v78, v96, v97
	v_cndmask_b32_e64 v104, v186, v79, s[20:21]
	v_add_f32_e32 v79, v93, v105
	v_max3_f32 v78, v78, v102, v103
	v_cndmask_b32_e64 v105, v186, v79, s[22:23]
	v_max3_f32 v110, v78, v104, v105
	v_add_u32_e32 v78, 0x688, v133
	ds_read2_b32 v[78:79], v78 offset1:1
	v_add_u32_e32 v80, 0x690, v133
	v_add_u32_e32 v90, 0x698, v133
	v_add_u32_e32 v92, 0x6a0, v133
	ds_read2_b32 v[80:81], v80 offset1:1
	ds_read2_b32 v[90:91], v90 offset1:1
	ds_read2_b32 v[92:93], v92 offset1:1
	s_waitcnt lgkmcnt(3)
	v_add_f32_e32 v78, v82, v78
	v_cndmask_b32_e32 v111, v186, v78, vcc
	v_add_f32_e32 v78, v83, v79
	v_cndmask_b32_e64 v112, v186, v78, s[10:11]
	s_waitcnt lgkmcnt(2)
	v_add_f32_e32 v79, v84, v80
	v_max3_f32 v78, v110, v111, v112
	v_cndmask_b32_e64 v110, v186, v79, s[12:13]
	v_add_f32_e32 v79, v85, v81
	v_cndmask_b32_e64 v113, v186, v79, s[14:15]
	s_waitcnt lgkmcnt(1)
	v_add_f32_e32 v79, v98, v90
	v_cndmask_b32_e64 v203, v186, v79, s[16:17]
	v_add_f32_e32 v79, v99, v91
	v_cndmask_b32_e64 v204, v186, v79, s[18:19]
	s_waitcnt lgkmcnt(0)
	v_add_f32_e32 v79, v100, v92
	v_max3_f32 v78, v78, v110, v113
	v_cndmask_b32_e64 v205, v186, v79, s[20:21]
	v_add_f32_e32 v79, v101, v93
	v_max3_f32 v78, v78, v203, v204
	v_cndmask_b32_e64 v206, v186, v79, s[22:23]
	v_max3_f32 v90, v78, v205, v206
	v_add_u32_e32 v78, 0x704, v133
	ds_read2_b32 v[78:79], v78 offset1:1
	v_add_u32_e32 v80, 0x70c, v133
	v_add_u32_e32 v82, 0x714, v133
	v_add_u32_e32 v84, 0x71c, v133
	ds_read2_b32 v[80:81], v80 offset1:1
	ds_read2_b32 v[82:83], v82 offset1:1
	ds_read2_b32 v[84:85], v84 offset1:1
	s_waitcnt lgkmcnt(3)
	v_add_f32_e32 v78, v86, v78
	v_cndmask_b32_e32 v133, v186, v78, vcc
	v_add_f32_e32 v78, v87, v79
	s_waitcnt lgkmcnt(2)
	v_add_f32_e32 v79, v88, v80
	v_cndmask_b32_e64 v207, v186, v78, s[10:11]
	v_cndmask_b32_e64 v208, v186, v79, s[12:13]
	v_add_f32_e32 v79, v89, v81
	s_waitcnt lgkmcnt(1)
	v_add_f32_e32 v74, v74, v82
	v_max3_f32 v78, v90, v133, v207
	v_cndmask_b32_e64 v209, v186, v79, s[14:15]
	v_cndmask_b32_e64 v210, v186, v74, s[16:17]
	v_add_f32_e32 v74, v75, v83
	s_waitcnt lgkmcnt(0)
	v_add_f32_e32 v75, v76, v84
	v_max3_f32 v78, v78, v208, v209
	v_cndmask_b32_e64 v211, v186, v74, s[18:19]
	v_cndmask_b32_e64 v212, v186, v75, s[20:21]
	v_add_f32_e32 v75, v77, v85
	v_max3_f32 v74, v78, v210, v211
	v_cndmask_b32_e64 v213, v186, v75, s[22:23]
	v_max3_f32 v74, v74, v212, v213
	ds_bpermute_b32 v75, v179, v74
	v_add_u32_e32 v90, s46, v181
	s_add_u32 s0, s38, s0
	s_addc_u32 s1, s39, 0
	s_mov_b32 s14, s36
	s_waitcnt lgkmcnt(0)
	v_max_f32_e32 v75, v75, v75
	v_max_f32_e32 v74, v74, v75
	ds_bpermute_b32 v75, v180, v74
	s_mov_b32 s15, s35
	s_waitcnt lgkmcnt(0)
	v_max_f32_e32 v75, v75, v75
	v_max_f32_e32 v214, v74, v75
	v_sub_f32_e32 v74, v137, v214
	v_exp_f32_e32 v78, v74
	v_sub_f32_e32 v74, v139, v214
	v_exp_f32_e32 v79, v74
	v_sub_f32_e32 v74, v155, v214
	v_exp_f32_e32 v80, v74
	v_sub_f32_e32 v74, v157, v214
	v_exp_f32_e32 v81, v74
	v_sub_f32_e32 v75, v141, v214
	v_add_f32_e32 v74, 0, v78
	v_exp_f32_e32 v86, v75
	v_sub_f32_e32 v75, v187, v214
	v_add_f32_e32 v74, v79, v74
	v_exp_f32_e32 v87, v75
	v_sub_f32_e32 v75, v192, v214
	v_add_f32_e32 v74, v80, v74
	v_exp_f32_e32 v88, v75
	v_sub_f32_e32 v75, v129, v214
	v_add_f32_e32 v74, v81, v74
	v_exp_f32_e32 v89, v75
	v_sub_f32_e32 v75, v135, v214
	v_add_f32_e32 v74, v86, v74
	v_exp_f32_e32 v98, v75
	v_sub_f32_e32 v75, v193, v214
	v_add_f32_e32 v74, v87, v74
	v_exp_f32_e32 v99, v75
	v_sub_f32_e32 v75, v131, v214
	v_add_f32_e32 v74, v88, v74
	v_exp_f32_e32 v129, v75
	v_sub_f32_e32 v75, v194, v214
	v_add_f32_e32 v74, v89, v74
	v_exp_f32_e32 v131, v75
	v_sub_f32_e32 v75, v195, v214
	v_add_f32_e32 v74, v98, v74
	v_exp_f32_e32 v135, v75
	v_sub_f32_e32 v75, v196, v214
	v_add_f32_e32 v74, v99, v74
	v_exp_f32_e32 v137, v75
	v_sub_f32_e32 v75, v197, v214
	v_add_f32_e32 v74, v129, v74
	v_exp_f32_e32 v139, v75
	v_sub_f32_e32 v75, v198, v214
	v_add_f32_e32 v74, v131, v74
	v_exp_f32_e32 v141, v75
	v_sub_f32_e32 v75, v122, v214
	v_add_f32_e32 v74, v135, v74
	v_exp_f32_e32 v122, v75
	v_sub_f32_e32 v75, v123, v214
	v_add_f32_e32 v74, v137, v74
	v_exp_f32_e32 v123, v75
	v_sub_f32_e32 v75, v124, v214
	v_add_f32_e32 v74, v139, v74
	v_exp_f32_e32 v124, v75
	v_sub_f32_e32 v75, v125, v214
	v_add_f32_e32 v74, v141, v74
	v_exp_f32_e32 v125, v75
	v_sub_f32_e32 v75, v188, v214
	v_add_f32_e32 v74, v122, v74
	v_exp_f32_e32 v155, v75
	v_sub_f32_e32 v75, v189, v214
	v_add_f32_e32 v74, v123, v74
	v_exp_f32_e32 v157, v75
	v_sub_f32_e32 v75, v190, v214
	v_add_f32_e32 v74, v124, v74
	v_exp_f32_e32 v187, v75
	v_sub_f32_e32 v75, v191, v214
	v_add_f32_e32 v74, v125, v74
	v_exp_f32_e32 v188, v75
	v_sub_f32_e32 v75, v200, v214
	v_add_f32_e32 v74, v155, v74
	v_exp_f32_e32 v189, v75
	v_sub_f32_e32 v75, v201, v214
	v_add_f32_e32 v74, v157, v74
	v_exp_f32_e32 v190, v75
	v_sub_f32_e32 v75, v199, v214
	v_add_f32_e32 v74, v187, v74
	v_exp_f32_e32 v191, v75
	v_sub_f32_e32 v75, v202, v214
	v_add_f32_e32 v74, v188, v74
	v_exp_f32_e32 v192, v75
	v_sub_f32_e32 v75, v114, v214
	v_add_f32_e32 v74, v189, v74
	v_exp_f32_e32 v114, v75
	v_sub_f32_e32 v75, v115, v214
	v_add_f32_e32 v74, v190, v74
	v_exp_f32_e32 v115, v75
	v_sub_f32_e32 v75, v116, v214
	v_add_f32_e32 v74, v191, v74
	v_exp_f32_e32 v116, v75
	v_sub_f32_e32 v75, v117, v214
	v_add_f32_e32 v74, v192, v74
	v_exp_f32_e32 v117, v75
	v_sub_f32_e32 v75, v119, v214
	v_add_f32_e32 v74, v114, v74
	v_exp_f32_e32 v119, v75
	v_sub_f32_e32 v75, v120, v214
	v_add_f32_e32 v74, v115, v74
	v_exp_f32_e32 v120, v75
	v_sub_f32_e32 v75, v118, v214
	v_add_f32_e32 v74, v116, v74
	v_exp_f32_e32 v118, v75
	v_sub_f32_e32 v75, v121, v214
	v_add_f32_e32 v74, v117, v74
	v_exp_f32_e32 v121, v75
	v_sub_f32_e32 v75, v106, v214
	v_add_f32_e32 v74, v119, v74
	v_exp_f32_e32 v106, v75
	v_sub_f32_e32 v75, v107, v214
	v_add_f32_e32 v74, v120, v74
	v_exp_f32_e32 v107, v75
	v_sub_f32_e32 v75, v108, v214
	v_add_f32_e32 v74, v118, v74
	v_exp_f32_e32 v108, v75
	v_sub_f32_e32 v75, v109, v214
	v_add_f32_e32 v74, v121, v74
	v_exp_f32_e32 v109, v75
	v_sub_f32_e32 v75, v94, v214
	v_add_f32_e32 v74, v106, v74
	v_exp_f32_e32 v193, v75
	v_sub_f32_e32 v75, v95, v214
	v_add_f32_e32 v74, v107, v74
	v_exp_f32_e32 v194, v75
	v_sub_f32_e32 v75, v96, v214
	v_add_f32_e32 v74, v108, v74
	v_exp_f32_e32 v195, v75
	v_sub_f32_e32 v75, v97, v214
	v_add_f32_e32 v74, v109, v74
	v_exp_f32_e32 v196, v75
	v_add_f32_e32 v74, v193, v74
	v_add_f32_e32 v74, v194, v74
	v_add_f32_e32 v74, v195, v74
	v_add_f32_e32 v82, v196, v74
	v_sub_f32_e32 v74, v102, v214
	v_exp_f32_e32 v102, v74
	v_sub_f32_e32 v74, v103, v214
	v_exp_f32_e32 v103, v74
	v_sub_f32_e32 v91, v104, v214
	v_exp_f32_e32 v104, v91
	v_sub_f32_e32 v91, v105, v214
	v_exp_f32_e32 v105, v91
	v_add_f32_e32 v82, v102, v82
	v_add_f32_e32 v94, v103, v82
	v_add_f32_e32 v94, v104, v94
	v_sub_f32_e32 v100, v111, v214
	v_add_u32_e32 v111, s47, v181
	ds_read_b128 v[74:77], v90 offset:61440
	ds_read_b128 v[82:85], v90 offset:62464
	v_cvt_pk_bf16_f32 v78, v78, v79
	v_cvt_pk_bf16_f32 v79, v80, v81
	v_cvt_pk_bf16_f32 v80, v86, v87
	v_cvt_pk_bf16_f32 v81, v88, v89
	ds_read_b128 v[86:89], v90 offset:63488
	v_add_f32_e32 v197, v105, v94
	ds_read_b128 v[94:97], v111 offset:61440
	ds_read_b128 v[90:93], v90 offset:64512
	s_waitcnt lgkmcnt(4)
	v_mfma_f32_16x16x32_bf16 v[74:77], v[74:77], v[78:81], 0
	v_exp_f32_e32 v198, v100
	v_sub_f32_e32 v112, v112, v214
	v_exp_f32_e32 v112, v112
	s_waitcnt lgkmcnt(3)
	v_mfma_f32_16x16x32_bf16 v[82:85], v[82:85], v[78:81], 0
	v_sub_f32_e32 v110, v110, v214
	v_exp_f32_e32 v110, v110
	v_sub_f32_e32 v113, v113, v214
	s_waitcnt lgkmcnt(2)
	v_mfma_f32_16x16x32_bf16 v[86:89], v[86:89], v[78:81], 0
	v_exp_f32_e32 v113, v113
	s_waitcnt lgkmcnt(0)
	v_mfma_f32_16x16x32_bf16 v[78:81], v[90:93], v[78:81], 0
	v_cvt_pk_bf16_f32 v90, v98, v99
	ds_read_b128 v[98:101], v111 offset:62464
	v_cvt_pk_bf16_f32 v91, v129, v131
	v_cvt_pk_bf16_f32 v92, v135, v137
	v_cvt_pk_bf16_f32 v93, v139, v141
	v_add_u32_e32 v129, s45, v181
	s_nop 0
	v_mfma_f32_16x16x32_bf16 v[74:77], v[94:97], v[90:93], v[74:77]
	ds_read_b128 v[94:97], v111 offset:63488
	s_waitcnt lgkmcnt(1)
	v_mfma_f32_16x16x32_bf16 v[82:85], v[98:101], v[90:93], v[82:85]
	ds_read_b128 v[98:101], v111 offset:64512
	s_waitcnt lgkmcnt(1)
	v_mfma_f32_16x16x32_bf16 v[86:89], v[94:97], v[90:93], v[86:89]
	ds_read_b128 v[94:97], v129 offset:61440
	v_add_f32_e32 v111, v198, v197
	v_add_f32_e32 v111, v112, v111
	s_waitcnt lgkmcnt(1)
	v_mfma_f32_16x16x32_bf16 v[78:81], v[98:101], v[90:93], v[78:81]
	ds_read_b128 v[98:101], v129 offset:62464
	v_cvt_pk_bf16_f32 v90, v122, v123
	v_cvt_pk_bf16_f32 v91, v124, v125
	v_cvt_pk_bf16_f32 v92, v155, v157
	v_cvt_pk_bf16_f32 v93, v187, v188
	v_add_u32_e32 v124, s44, v181
	v_sub_f32_e32 v122, v203, v214
	s_waitcnt lgkmcnt(1)
	v_mfma_f32_16x16x32_bf16 v[74:77], v[94:97], v[90:93], v[74:77]
	ds_read_b128 v[94:97], v129 offset:63488
	v_exp_f32_e32 v122, v122
	v_sub_f32_e32 v123, v204, v214
	s_waitcnt lgkmcnt(1)
	v_mfma_f32_16x16x32_bf16 v[82:85], v[98:101], v[90:93], v[82:85]
	ds_read_b128 v[98:101], v129 offset:64512
	v_exp_f32_e32 v123, v123
	v_sub_f32_e32 v125, v205, v214
	s_waitcnt lgkmcnt(1)
	v_mfma_f32_16x16x32_bf16 v[86:89], v[94:97], v[90:93], v[86:89]
	ds_read_b128 v[94:97], v124 offset:61440
	v_add_f32_e32 v111, v110, v111
	v_add_f32_e32 v111, v113, v111
	s_waitcnt lgkmcnt(1)
	v_mfma_f32_16x16x32_bf16 v[78:81], v[98:101], v[90:93], v[78:81]
	ds_read_b128 v[98:101], v124 offset:62464
	v_cvt_pk_bf16_f32 v90, v189, v190
	v_cvt_pk_bf16_f32 v91, v191, v192
	v_cvt_pk_bf16_f32 v92, v114, v115
	v_cvt_pk_bf16_f32 v93, v116, v117
	v_add_u32_e32 v117, s43, v181
	v_exp_f32_e32 v114, v125
	s_waitcnt lgkmcnt(1)
	v_mfma_f32_16x16x32_bf16 v[74:77], v[94:97], v[90:93], v[74:77]
	ds_read_b128 v[94:97], v124 offset:63488
	v_sub_f32_e32 v115, v206, v214
	v_exp_f32_e32 v115, v115
	s_waitcnt lgkmcnt(1)
	v_mfma_f32_16x16x32_bf16 v[82:85], v[98:101], v[90:93], v[82:85]
	ds_read_b128 v[98:101], v124 offset:64512
	v_sub_f32_e32 v116, v133, v214
	v_add_f32_e32 v111, v122, v111
	s_waitcnt lgkmcnt(1)
	v_mfma_f32_16x16x32_bf16 v[86:89], v[94:97], v[90:93], v[86:89]
	ds_read_b128 v[94:97], v117 offset:61440
	v_exp_f32_e32 v116, v116
	v_add_f32_e32 v111, v123, v111
	s_waitcnt lgkmcnt(1)
	v_mfma_f32_16x16x32_bf16 v[78:81], v[98:101], v[90:93], v[78:81]
	ds_read_b128 v[98:101], v117 offset:62464
	v_cvt_pk_bf16_f32 v90, v119, v120
	v_cvt_pk_bf16_f32 v91, v118, v121
	v_cvt_pk_bf16_f32 v92, v106, v107
	v_cvt_pk_bf16_f32 v93, v108, v109
	v_add_u32_e32 v109, s42, v181
	v_add_f32_e32 v111, v114, v111
	s_waitcnt lgkmcnt(1)
	v_mfma_f32_16x16x32_bf16 v[74:77], v[94:97], v[90:93], v[74:77]
	ds_read_b128 v[94:97], v117 offset:63488
	v_sub_f32_e32 v124, v207, v214
	v_add_f32_e32 v111, v115, v111
	s_waitcnt lgkmcnt(1)
	v_mfma_f32_16x16x32_bf16 v[82:85], v[98:101], v[90:93], v[82:85]
	ds_read_b128 v[98:101], v117 offset:64512
	v_exp_f32_e32 v106, v124
	v_sub_f32_e32 v107, v208, v214
	s_waitcnt lgkmcnt(1)
	v_mfma_f32_16x16x32_bf16 v[86:89], v[94:97], v[90:93], v[86:89]
	ds_read_b128 v[94:97], v109 offset:61440
	v_exp_f32_e32 v107, v107
	v_add_f32_e32 v108, v116, v111
	s_waitcnt lgkmcnt(1)
	v_mfma_f32_16x16x32_bf16 v[78:81], v[98:101], v[90:93], v[78:81]
	ds_read_b128 v[98:101], v109 offset:62464
	v_cvt_pk_bf16_f32 v90, v193, v194
	v_cvt_pk_bf16_f32 v91, v195, v196
	v_cvt_pk_bf16_f32 v92, v102, v103
	v_cvt_pk_bf16_f32 v93, v104, v105
	v_add_u32_e32 v105, s41, v181
	v_sub_f32_e32 v111, v209, v214
	s_waitcnt lgkmcnt(1)
	v_mfma_f32_16x16x32_bf16 v[74:77], v[94:97], v[90:93], v[74:77]
	ds_read_b128 v[94:97], v109 offset:63488
	v_exp_f32_e32 v111, v111
	v_add_f32_e32 v108, v106, v108
	s_waitcnt lgkmcnt(1)
	v_mfma_f32_16x16x32_bf16 v[82:85], v[98:101], v[90:93], v[82:85]
	ds_read_b128 v[98:101], v109 offset:64512
	v_sub_f32_e32 v102, v210, v214
	v_add_f32_e32 v108, v107, v108
	s_waitcnt lgkmcnt(1)
	v_mfma_f32_16x16x32_bf16 v[86:89], v[94:97], v[90:93], v[86:89]
	ds_read_b128 v[94:97], v105 offset:61440
	v_exp_f32_e32 v102, v102
	v_sub_f32_e32 v104, v211, v214
	s_waitcnt lgkmcnt(1)
	v_mfma_f32_16x16x32_bf16 v[78:81], v[98:101], v[90:93], v[78:81]
	ds_read_b128 v[98:101], v105 offset:62464
	v_add_f32_e32 v103, v111, v108
	v_exp_f32_e32 v104, v104
	v_sub_f32_e32 v108, v212, v214
	v_cvt_pk_bf16_f32 v90, v198, v112
	v_cvt_pk_bf16_f32 v91, v110, v113
	v_cvt_pk_bf16_f32 v92, v122, v123
	v_cvt_pk_bf16_f32 v93, v114, v115
	v_exp_f32_e32 v108, v108
	v_sub_f32_e32 v109, v213, v214
	s_waitcnt lgkmcnt(1)
	v_mfma_f32_16x16x32_bf16 v[74:77], v[94:97], v[90:93], v[74:77]
	ds_read_b128 v[94:97], v105 offset:63488
	v_exp_f32_e32 v109, v109
	v_add_f32_e32 v103, v102, v103
	s_waitcnt lgkmcnt(1)
	v_mfma_f32_16x16x32_bf16 v[82:85], v[98:101], v[90:93], v[82:85]
	ds_read_b128 v[98:101], v105 offset:64512
	v_add_f32_e32 v103, v104, v103
	v_add_f32_e32 v103, v108, v103
	v_add_f32_e32 v103, v109, v103
	ds_bpermute_b32 v105, v179, v103
	s_waitcnt lgkmcnt(1)
	v_mfma_f32_16x16x32_bf16 v[78:81], v[98:101], v[90:93], v[78:81]
	v_cvt_pk_bf16_f32 v100, v102, v104
	v_lshlrev_b32_e32 v102, 2, v144
	v_lshl_or_b32 v120, s37, 8, v102
	s_waitcnt lgkmcnt(0)
	v_add_f32_e32 v112, v103, v105
	global_load_dwordx4 v[102:105], v120, s[72:73]
	global_load_dwordx4 v[240:243], v120, s[72:73] offset:64
	global_load_dwordx4 v[244:247], v120, s[72:73] offset:128
	global_load_dwordx4 v[248:251], v120, s[72:73] offset:192
	v_add_u32_e32 v110, s40, v181
	v_mfma_f32_16x16x32_bf16 v[86:89], v[94:97], v[90:93], v[86:89]
	ds_read_b128 v[94:97], v110 offset:61440
	ds_read_b128 v[90:93], v110 offset:62464
	v_cvt_pk_bf16_f32 v98, v116, v106
	v_cvt_pk_bf16_f32 v99, v107, v111
	v_cvt_pk_bf16_f32 v101, v108, v109
	ds_bpermute_b32 v106, v180, v112
	v_and_b32_e32 v113, 0xffff0000, v163
	s_waitcnt lgkmcnt(2)
	v_mfma_f32_16x16x32_bf16 v[94:97], v[94:97], v[98:101], v[74:77]
	v_mov_b32_e32 v157, v127
	s_nop 1
	ds_read_b128 v[74:77], v110 offset:63488
	s_waitcnt lgkmcnt(2)
	v_mfma_f32_16x16x32_bf16 v[82:85], v[90:93], v[98:101], v[82:85]
	ds_read_b128 v[90:93], v110 offset:64512
	s_waitcnt lgkmcnt(1)
	v_mfma_f32_16x16x32_bf16 v[86:89], v[74:77], v[98:101], v[86:89]
	v_add_f32_e32 v74, v112, v106
	v_rcp_f32_e32 v106, v74
	v_lshlrev_b32_e32 v112, 16, v163
	s_waitcnt lgkmcnt(0)
	v_mfma_f32_16x16x32_bf16 v[76:79], v[90:93], v[98:101], v[78:81]
	v_lshlrev_b32_e32 v100, 16, v162
	v_pk_mul_f32 v[96:97], v[96:97], v[106:107] op_sel_hi:[1,0]
	v_pk_mul_f32 v[94:95], v[94:95], v[106:107] op_sel_hi:[1,0]
	v_and_b32_e32 v101, 0xffff0000, v162
	v_mul_f32_e32 v108, 0xbfb8aa3b, v101
	s_nop 2
	v_pk_mul_f32 v[76:77], v[76:77], v[106:107] op_sel_hi:[1,0]
	v_pk_mul_f32 v[74:75], v[78:79], v[106:107] op_sel_hi:[1,0]
	v_mul_f32_e32 v107, 0xbfb8aa3b, v100
	v_exp_f32_e32 v107, v107
	v_exp_f32_e32 v111, v108
	v_pk_mul_f32 v[108:109], v[94:95], v[94:95]
	v_pk_mul_f32 v[98:99], v[96:97], v[96:97]
	v_add_f32_e32 v107, 1.0, v107
	v_rcp_f32_e32 v110, v107
	v_add_f32_e32 v107, 1.0, v111
	v_add_f32_e32 v108, v108, v109
	v_pk_mul_f32 v[82:83], v[82:83], v[106:107] op_sel_hi:[1,0]
	v_add_f32_e32 v98, v98, v108
	v_pk_mul_f32 v[116:117], v[82:83], v[82:83]
	v_add_f32_e32 v98, v99, v98
	v_pk_mul_f32 v[84:85], v[84:85], v[106:107] op_sel_hi:[1,0]
	v_add_f32_e32 v98, v116, v98
	v_pk_mul_f32 v[114:115], v[84:85], v[84:85]
	v_add_f32_e32 v98, v117, v98
	v_pk_mul_f32 v[86:87], v[86:87], v[106:107] op_sel_hi:[1,0]
	v_add_f32_e32 v98, v114, v98
	v_rcp_f32_e32 v111, v107
	v_pk_mul_f32 v[88:89], v[88:89], v[106:107] op_sel_hi:[1,0]
	v_pk_mul_f32 v[106:107], v[86:87], v[86:87]
	v_add_f32_e32 v98, v115, v98
	v_add_f32_e32 v98, v106, v98
	v_pk_mul_f32 v[118:119], v[88:89], v[88:89]
	v_add_f32_e32 v98, v107, v98
	v_add_f32_e32 v98, v118, v98
	v_pk_mul_f32 v[80:81], v[76:77], v[76:77]
	v_add_f32_e32 v98, v119, v98
	v_add_f32_e32 v80, v80, v98
	v_pk_mul_f32 v[78:79], v[74:75], v[74:75]
	v_add_f32_e32 v80, v81, v80
	v_add_f32_e32 v78, v78, v80
	v_add_f32_e32 v78, v79, v78
	ds_bpermute_b32 v79, v179, v78
	v_mul_f32_e32 v80, 0xbfb8aa3b, v112
	v_exp_f32_e32 v80, v80
	v_mul_f32_e32 v81, 0xbfb8aa3b, v113
	v_exp_f32_e32 v81, v81
	s_waitcnt lgkmcnt(0)
	v_add_f32_e32 v98, v78, v79
	ds_bpermute_b32 v99, v180, v98
	v_add_f32_e32 v78, 1.0, v80
	v_add_f32_e32 v79, 1.0, v81
	v_lshl_add_u64 v[90:91], s[0:1], 0, v[156:157]
	v_lshlrev_b32_e32 v92, 1, v144
	s_waitcnt lgkmcnt(0)
	v_add_f32_e32 v80, v98, v99
	v_fmamk_f32 v80, v80, 0x3c800000, v185
	v_mul_f32_e32 v81, 0x4b800000, v80
	v_cmp_gt_f32_e32 vcc, s34, v80
	v_mov_b32_e32 v93, v127
	v_lshl_add_u64 v[90:91], v[90:91], 0, v[92:93]
	v_cndmask_b32_e32 v80, v80, v81, vcc
	v_rsq_f32_e32 v98, v80
	v_rcp_f32_e32 v78, v78
	v_rcp_f32_e32 v79, v79
	v_pk_mul_f32 v[80:81], v[110:111], v[100:101]
	v_mul_f32_e32 v92, 0x45800000, v98
	v_cndmask_b32_e32 v92, v98, v92, vcc
	v_pk_mul_f32 v[94:95], v[94:95], v[92:93] op_sel_hi:[1,0]
	v_pk_mul_f32 v[78:79], v[78:79], v[112:113]
	s_waitcnt vmcnt(0)
	v_pk_mul_f32 v[94:95], v[102:103], v[94:95]
	v_lshlrev_b32_e32 v98, 16, v161
	v_pk_mul_f32 v[80:81], v[80:81], v[94:95]
	v_pk_mul_f32 v[94:95], v[96:97], v[92:93] op_sel_hi:[1,0]
	v_cvt_pk_bf16_f32 v80, v80, v81
	v_pk_mul_f32 v[94:95], v[104:105], v[94:95]
	v_and_b32_e32 v99, 0xffff0000, v161
	v_pk_mul_f32 v[78:79], v[78:79], v[94:95]
	v_lshlrev_b32_e32 v94, 16, v160
	v_cvt_pk_bf16_f32 v81, v78, v79
	global_store_dwordx2 v[90:91], v[80:81], off
	v_and_b32_e32 v95, 0xffff0000, v160
	v_mul_f32_e32 v93, 0xbfb8aa3b, v94
	v_exp_f32_e32 v93, v93
	v_mul_f32_e32 v96, 0xbfb8aa3b, v95
	v_exp_f32_e32 v97, v96
	s_and_b64 vcc, exec, s[28:29]
	v_add_f32_e32 v93, 1.0, v93
	v_rcp_f32_e32 v96, v93
	v_add_f32_e32 v93, 1.0, v97
	v_mul_f32_e32 v97, 0xbfb8aa3b, v98
	v_exp_f32_e32 v100, v97
	v_mul_f32_e32 v97, 0xbfb8aa3b, v99
	v_exp_f32_e32 v101, v97
	v_rcp_f32_e32 v97, v93
	v_add_f32_e32 v93, 1.0, v100
	v_rcp_f32_e32 v100, v93
	v_add_f32_e32 v93, 1.0, v101
	v_rcp_f32_e32 v101, v93
	v_pk_mul_f32 v[82:83], v[82:83], v[92:93] op_sel_hi:[1,0]
	v_pk_mul_f32 v[94:95], v[96:97], v[94:95]
	v_pk_mul_f32 v[76:77], v[76:77], v[92:93] op_sel_hi:[1,0]
	v_pk_mul_f32 v[96:97], v[100:101], v[98:99]
	v_pk_mul_f32 v[74:75], v[74:75], v[92:93] op_sel_hi:[1,0]
	v_mov_b64_e32 v[160:161], v[166:167]
	v_mov_b64_e32 v[162:163], v[164:165]
	v_pk_mul_f32 v[78:79], v[240:241], v[82:83]
	v_pk_mul_f32 v[82:83], v[84:85], v[92:93] op_sel_hi:[1,0]
	v_pk_mul_f32 v[78:79], v[94:95], v[78:79]
	v_pk_mul_f32 v[80:81], v[242:243], v[82:83]
	v_cvt_pk_bf16_f32 v78, v78, v79
	v_pk_mul_f32 v[80:81], v[96:97], v[80:81]
	v_lshlrev_b32_e32 v82, 16, v158
	v_cvt_pk_bf16_f32 v79, v80, v81
	global_store_dwordx2 v[90:91], v[78:79], off offset:32
	v_and_b32_e32 v83, 0xffff0000, v158
	v_mul_f32_e32 v84, 0xbfb8aa3b, v82
	v_mul_f32_e32 v85, 0xbfb8aa3b, v83
	v_exp_f32_e32 v84, v84
	v_exp_f32_e32 v85, v85
	v_add_f32_e32 v84, 1.0, v84
	v_add_f32_e32 v85, 1.0, v85
	v_rcp_f32_e32 v84, v84
	v_rcp_f32_e32 v85, v85
	s_nop 0
	v_pk_mul_f32 v[82:83], v[84:85], v[82:83]
	v_pk_mul_f32 v[84:85], v[86:87], v[92:93] op_sel_hi:[1,0]
	v_pk_mul_f32 v[78:79], v[244:245], v[84:85]
	v_lshlrev_b32_e32 v84, 16, v159
	v_and_b32_e32 v85, 0xffff0000, v159
	v_mul_f32_e32 v86, 0xbfb8aa3b, v84
	v_mul_f32_e32 v87, 0xbfb8aa3b, v85
	v_exp_f32_e32 v86, v86
	v_exp_f32_e32 v87, v87
	v_pk_mul_f32 v[78:79], v[82:83], v[78:79]
	v_mov_b64_e32 v[158:159], v[168:169]
	v_add_f32_e32 v82, 1.0, v86
	v_add_f32_e32 v83, 1.0, v87
	v_rcp_f32_e32 v82, v82
	v_rcp_f32_e32 v83, v83
	v_pk_mul_f32 v[86:87], v[88:89], v[92:93] op_sel_hi:[1,0]
	v_cvt_pk_bf16_f32 v78, v78, v79
	v_pk_mul_f32 v[80:81], v[246:247], v[86:87]
	v_pk_mul_f32 v[82:83], v[82:83], v[84:85]
	s_nop 0
	v_pk_mul_f32 v[80:81], v[82:83], v[80:81]
	v_lshlrev_b32_e32 v82, 16, v146
	v_cvt_pk_bf16_f32 v79, v80, v81
	global_store_dwordx2 v[90:91], v[78:79], off offset:64
	v_and_b32_e32 v83, 0xffff0000, v146
	v_mul_f32_e32 v84, 0xbfb8aa3b, v82
	v_mul_f32_e32 v85, 0xbfb8aa3b, v83
	v_exp_f32_e32 v84, v84
	v_exp_f32_e32 v85, v85
	v_add_f32_e32 v84, 1.0, v84
	v_add_f32_e32 v85, 1.0, v85
	v_rcp_f32_e32 v84, v84
	v_rcp_f32_e32 v85, v85
	v_pk_mul_f32 v[76:77], v[248:249], v[76:77]
	v_pk_mul_f32 v[78:79], v[84:85], v[82:83]
	v_lshlrev_b32_e32 v82, 16, v147
	v_and_b32_e32 v83, 0xffff0000, v147
	v_mul_f32_e32 v84, 0xbfb8aa3b, v82
	v_mul_f32_e32 v85, 0xbfb8aa3b, v83
	v_exp_f32_e32 v84, v84
	v_exp_f32_e32 v85, v85
	v_pk_mul_f32 v[76:77], v[78:79], v[76:77]
	v_pk_mul_f32 v[74:75], v[250:251], v[74:75]
	v_add_f32_e32 v78, 1.0, v84
	v_add_f32_e32 v79, 1.0, v85
	v_rcp_f32_e32 v78, v78
	v_rcp_f32_e32 v79, v79
	v_cvt_pk_bf16_f32 v76, v76, v77
	v_mov_b64_e32 v[146:147], v[170:171]
	v_pk_mul_f32 v[78:79], v[78:79], v[82:83]
	s_nop 0
	v_pk_mul_f32 v[74:75], v[78:79], v[74:75]
	v_mov_b64_e32 v[80:81], v[68:69]
	v_cvt_pk_bf16_f32 v77, v74, v75
	global_store_dwordx2 v[90:91], v[76:77], off offset:96
	v_mov_b64_e32 v[76:77], v[72:73]
	v_mov_b64_e32 v[74:75], v[70:71]
	v_mov_b64_e32 v[78:79], v[66:67]
	s_cbranch_vccnz .LBB0_461
